# spatial gating: LayerNorm gain/bias vectors loaded once per workgroup into AGPRs instead of four dependent load rounds per tile
# speedup vs baseline: 1.0094x; 1.0028x over previous
.LBB0_1206:
	s_mov_b64 s[64:65], -1
	s_cmp_lt_i32 s90, 13
	s_cselect_b64 s[0:1], -1, 0
	s_cmp_gt_i32 s91, 12
	s_cselect_b64 s[4:5], -1, 0
	s_and_b64 s[0:1], s[0:1], s[4:5]
	s_andn2_b64 vcc, exec, s[0:1]
	s_cbranch_vccnz .LBB0_1266
	s_waitcnt lgkmcnt(0)
	s_load_dword s3, s[96:97], 0x128
	s_add_u32 s4, s96, 0x128
	s_addc_u32 s5, s97, 0
	s_cmpk_gt_i32 s2, 0x3ff
	s_cbranch_scc1 .LBB0_1212
	v_readlane_b32 s8, v126, 2
	v_readlane_b32 s14, v126, 8
	v_readlane_b32 s15, v126, 9
	s_add_u32 s6, s14, 0x191e8000
	s_addc_u32 s7, s15, 0
	v_readlane_b32 s9, v126, 3
	s_add_u32 s8, s14, 0x18c00000
	v_readlane_b32 s10, v126, 4
	s_addc_u32 s9, s15, 0
	v_readlane_b32 s11, v126, 5
	s_add_u32 s10, s14, 0x233e8000
	v_readlane_b32 s13, v126, 7
	s_addc_u32 s11, s15, 0
	s_add_u32 s13, s14, 0x213e8000
	s_addc_u32 s18, s15, 0
	v_readlane_b32 s12, v126, 6
	s_add_u32 s19, s14, 0x253e8000
	s_addc_u32 s20, s15, 0
	s_lshl_b32 s21, s2, 7
	s_waitcnt lgkmcnt(0)
	s_lshl_b32 s22, s3, 7
	s_lshl_b32 s23, s2, 4
	s_lshl_b32 s24, s3, 4
	s_movk_i32 s25, 0x80
	s_mov_b32 s12, 0x3a800000
	s_mov_b32 s15, 0
	s_mov_b32 s26, 0x800000
	s_waitcnt vmcnt(0)
	v_mov_b32_e32 v25, 0
	s_movk_i32 s27, 0x110
	s_mov_b32 s28, s2
	s_branch .LBB0_1210
.LBB0_1209:
	s_or_b64 exec, exec, s[0:1]
	s_and_b32 s30, s21, 0x380
	v_ashrrev_i32_e32 v6, 4, v26
	v_add_u32_e32 v4, 0x200, v26
	v_and_b32_e32 v38, 15, v26
	v_add_u32_e32 v2, s30, v6
	v_ashrrev_i32_e32 v7, 4, v4
	v_lshlrev_b32_e32 v24, 4, v38
	v_ashrrev_i32_e32 v3, 31, v2
	v_add_u32_e32 v4, s30, v7
	v_lshl_add_u64 v[0:1], s[8:9], 0, v[24:25]
	v_lshlrev_b64 v[2:3], 8, v[2:3]
	v_ashrrev_i32_e32 v5, 31, v4
	v_lshl_add_u64 v[2:3], v[0:1], 0, v[2:3]
	v_lshlrev_b64 v[4:5], 8, v[4:5]
	v_lshl_add_u64 v[4:5], v[0:1], 0, v[4:5]
	global_load_dwordx4 v[16:19], v[2:3], off
	global_load_dwordx4 v[28:31], v[4:5], off
	v_add_u32_e32 v2, 0x400, v26
	v_ashrrev_i32_e32 v8, 4, v2
	v_add_u32_e32 v4, 0x600, v26
	v_add_u32_e32 v2, s30, v8
	v_ashrrev_i32_e32 v9, 4, v4
	v_ashrrev_i32_e32 v3, 31, v2
	v_add_u32_e32 v4, s30, v9
	v_lshlrev_b64 v[2:3], 8, v[2:3]
	v_ashrrev_i32_e32 v5, 31, v4
	v_lshl_add_u64 v[2:3], v[0:1], 0, v[2:3]
	v_lshlrev_b64 v[4:5], 8, v[4:5]
	v_lshl_add_u64 v[0:1], v[0:1], 0, v[4:5]
	global_load_dwordx4 v[32:35], v[2:3], off
	global_load_dwordx4 v[40:43], v[0:1], off
	v_and_b32_e32 v39, 0x7f, v26
	v_or_b32_e32 v0, s29, v39
	v_ashrrev_i32_e32 v1, 31, v0
	v_lshlrev_b64 v[0:1], 11, v[0:1]
	s_lshl_b32 s14, s30, 1
	v_and_b32_e32 v14, -8, v6
	s_lshl_b32 s31, s30, 2
	v_lshl_add_u64 v[0:1], s[10:11], 0, v[0:1]
	v_add_u32_e32 v2, 0, v24
	v_ashrrev_i32_e32 v15, 31, v14
	s_add_u32 s0, s66, s31
	v_lshl_add_u64 v[0:1], v[0:1], 0, s[14:15]
	v_mad_u64_u32 v[36:37], s[16:17], v6, s27, v[2:3]
	v_mad_u64_u32 v[48:49], s[16:17], v7, s27, v[2:3]
	v_mad_u64_u32 v[50:51], s[16:17], v8, s27, v[2:3]
	v_mad_u64_u32 v[52:53], s[16:17], v9, s27, v[2:3]
	v_lshl_add_u64 v[2:3], v[14:15], 1, v[0:1]
	s_addc_u32 s1, s67, 0
	v_and_b32_e32 v12, -8, v7
	v_and_b32_e32 v20, -8, v8
	v_and_b32_e32 v22, -8, v9
	global_load_dwordx4 v[44:47], v[2:3], off
	s_add_u32 s16, s68, s31
	v_ashrrev_i32_e32 v13, 31, v12
	v_ashrrev_i32_e32 v21, 31, v20
	v_ashrrev_i32_e32 v23, 31, v22
	v_lshlrev_b64 v[2:3], 2, v[14:15]
	s_addc_u32 s17, s69, 0
	v_lshl_add_u64 v[4:5], v[12:13], 1, v[0:1]
	v_lshl_add_u64 v[6:7], v[20:21], 1, v[0:1]
	v_lshl_add_u64 v[0:1], v[22:23], 1, v[0:1]
	v_lshl_add_u64 v[56:57], s[16:17], 0, v[2:3]
	v_lshl_add_u64 v[54:55], s[0:1], 0, v[2:3]
	global_load_dwordx4 v[8:11], v[4:5], off
	s_nop 0
	global_load_dwordx4 v[4:7], v[6:7], off
	s_nop 0
	global_load_dwordx4 v[0:3], v[0:1], off
	v_lshl_add_u32 v15, v39, 2, 0
	v_add_u32_e32 v27, 0x11000, v15
	s_waitcnt vmcnt(7)
	ds_write_b128 v36, v[16:19]
	s_waitcnt vmcnt(6)
	ds_write_b128 v48, v[28:31]
	s_waitcnt vmcnt(5)
	ds_write_b128 v50, v[32:35]
	s_waitcnt vmcnt(4)
	ds_write_b128 v52, v[40:43]
	s_waitcnt lgkmcnt(0)
	s_barrier
	s_mov_b64 exec, s[64:65]
	global_load_dwordx4 a[52:55], v[56:57], off
	global_load_dwordx4 a[56:59], v[54:55], off
	global_load_dwordx4 a[60:63], v[54:55], off offset:16
	global_load_dwordx4 a[64:67], v[56:57], off offset:16
	s_mov_b64 exec, -1
	v_add_u32_e32 v28, 0x11200, v15
	v_lshlrev_b64 v[48:49], 2, v[12:13]
	ds_read_b32 v13, v27
	ds_read_b32 v15, v28
	v_lshl_add_u64 v[50:51], s[0:1], 0, v[48:49]
	v_lshl_add_u64 v[48:49], s[16:17], 0, v[48:49]
	s_waitcnt vmcnt(7)
	v_lshlrev_b32_e32 v24, 16, v44
	v_and_b32_e32 v29, 0xffff0000, v44
	v_lshlrev_b32_e32 v44, 16, v45
	v_and_b32_e32 v45, 0xffff0000, v45
	v_lshlrev_b32_e32 v52, 16, v46
	v_and_b32_e32 v46, 0xffff0000, v46
	v_lshlrev_b32_e32 v53, 16, v47
	v_and_b32_e32 v47, 0xffff0000, v47
	s_waitcnt lgkmcnt(1)
	v_sub_f32_e32 v24, v24, v13
	v_sub_f32_e32 v29, v29, v13
	v_sub_f32_e32 v44, v44, v13
	v_sub_f32_e32 v45, v45, v13
	v_sub_f32_e32 v52, v52, v13
	v_sub_f32_e32 v46, v46, v13
	v_sub_f32_e32 v53, v53, v13
	v_sub_f32_e32 v13, v47, v13
	s_waitcnt lgkmcnt(0)
	v_mul_f32_e32 v24, v24, v15
	v_mul_f32_e32 v29, v29, v15
	v_mul_f32_e32 v44, v44, v15
	v_mul_f32_e32 v45, v45, v15
	v_mul_f32_e32 v47, v52, v15
	v_mul_f32_e32 v52, v53, v15
	v_mul_f32_e32 v13, v13, v15
	v_mul_f32_e32 v46, v46, v15
	s_waitcnt vmcnt(2)
	v_accvgpr_read_b32 v16, a52
	v_accvgpr_read_b32 v17, a53
	v_accvgpr_read_b32 v18, a54
	v_accvgpr_read_b32 v19, a55
	v_accvgpr_read_b32 v30, a56
	v_accvgpr_read_b32 v31, a57
	v_accvgpr_read_b32 v32, a58
	v_accvgpr_read_b32 v33, a59
	v_fma_f32 v15, v30, v24, v16
	v_fma_f32 v16, v31, v29, v17
	v_fma_f32 v17, v32, v44, v18
	v_fmac_f32_e32 v19, v33, v45
	s_waitcnt vmcnt(0)
	v_accvgpr_read_b32 v34, a60
	v_accvgpr_read_b32 v35, a61
	v_accvgpr_read_b32 v36, a62
	v_accvgpr_read_b32 v37, a63
	v_accvgpr_read_b32 v40, a64
	v_accvgpr_read_b32 v41, a65
	v_accvgpr_read_b32 v42, a66
	v_accvgpr_read_b32 v43, a67
	v_fma_f32 v18, v34, v47, v40
	v_fma_f32 v29, v36, v52, v42
	v_fmac_f32_e32 v43, v37, v13
	v_fma_f32 v24, v35, v46, v41
	v_cvt_pk_bf16_f32 v13, v15, v16
	v_cvt_pk_bf16_f32 v52, v17, v19
	v_cvt_pk_bf16_f32 v53, v18, v24
	v_cvt_pk_bf16_f32 v29, v29, v43
	s_mov_b64 exec, s[64:65]
	global_load_dwordx4 a[68:71], v[48:49], off
	global_load_dwordx4 a[72:75], v[50:51], off
	global_load_dwordx4 a[76:79], v[50:51], off offset:16
	global_load_dwordx4 a[80:83], v[48:49], off offset:16
	s_mov_b64 exec, -1
	ds_read_b32 v49, v27
	ds_read_b32 v50, v28
	v_lshl_add_u32 v24, v39, 1, 0
	v_mad_u64_u32 v[14:15], s[34:35], v14, s27, v[24:25]
	v_lshlrev_b64 v[44:45], 2, v[20:21]
	v_lshlrev_b32_e32 v15, 16, v8
	v_and_b32_e32 v8, 0xffff0000, v8
	v_lshlrev_b32_e32 v21, 16, v9
	v_and_b32_e32 v9, 0xffff0000, v9
	v_lshlrev_b32_e32 v39, 16, v10
	v_and_b32_e32 v10, 0xffff0000, v10
	v_lshlrev_b32_e32 v48, 16, v11
	v_and_b32_e32 v11, 0xffff0000, v11
	ds_write_b16 v14, v13 offset:34816
	ds_write_b16_d16_hi v14, v13 offset:35088
	ds_write_b16 v14, v52 offset:35360
	ds_write_b16_d16_hi v14, v52 offset:35632
	ds_write_b16 v14, v53 offset:35904
	ds_write_b16_d16_hi v14, v53 offset:36176
	ds_write_b16 v14, v29 offset:36448
	ds_write_b16_d16_hi v14, v29 offset:36720
	s_waitcnt lgkmcnt(9)
	v_sub_f32_e32 v13, v15, v49
	v_sub_f32_e32 v8, v8, v49
	v_sub_f32_e32 v14, v21, v49
	v_sub_f32_e32 v9, v9, v49
	v_sub_f32_e32 v15, v39, v49
	v_sub_f32_e32 v10, v10, v49
	v_sub_f32_e32 v21, v48, v49
	v_sub_f32_e32 v11, v11, v49
	s_waitcnt lgkmcnt(8)
	v_mul_f32_e32 v8, v8, v50
	v_mul_f32_e32 v14, v14, v50
	v_mul_f32_e32 v9, v9, v50
	v_mul_f32_e32 v15, v15, v50
	v_mul_f32_e32 v10, v10, v50
	v_mul_f32_e32 v21, v21, v50
	v_lshl_add_u64 v[46:47], s[0:1], 0, v[44:45]
	v_lshl_add_u64 v[44:45], s[16:17], 0, v[44:45]
	v_mul_f32_e32 v13, v13, v50
	v_mul_f32_e32 v11, v11, v50
	s_waitcnt vmcnt(2)
	v_accvgpr_read_b32 v16, a68
	v_accvgpr_read_b32 v17, a69
	v_accvgpr_read_b32 v18, a70
	v_accvgpr_read_b32 v19, a71
	v_accvgpr_read_b32 v30, a72
	v_accvgpr_read_b32 v31, a73
	v_accvgpr_read_b32 v32, a74
	v_accvgpr_read_b32 v33, a75
	v_fma_f32 v8, v31, v8, v17
	v_fma_f32 v14, v32, v14, v18
	v_fmac_f32_e32 v19, v33, v9
	s_waitcnt vmcnt(0)
	v_accvgpr_read_b32 v34, a76
	v_accvgpr_read_b32 v35, a77
	v_accvgpr_read_b32 v36, a78
	v_accvgpr_read_b32 v37, a79
	v_accvgpr_read_b32 v40, a80
	v_accvgpr_read_b32 v41, a81
	v_accvgpr_read_b32 v42, a82
	v_accvgpr_read_b32 v43, a83
	v_fma_f32 v9, v34, v15, v40
	v_fma_f32 v10, v35, v10, v41
	v_fma_f32 v15, v36, v21, v42
	v_fma_f32 v13, v30, v13, v16
	v_fmac_f32_e32 v43, v37, v11
	v_cvt_pk_bf16_f32 v21, v13, v8
	v_cvt_pk_bf16_f32 v29, v14, v19
	v_cvt_pk_bf16_f32 v39, v9, v10
	v_cvt_pk_bf16_f32 v48, v15, v43
	s_mov_b64 exec, s[64:65]
	global_load_dwordx4 a[84:87], v[44:45], off
	global_load_dwordx4 a[88:91], v[46:47], off
	global_load_dwordx4 a[92:95], v[46:47], off offset:16
	global_load_dwordx4 a[96:99], v[44:45], off offset:16
	s_mov_b64 exec, -1
	ds_read_b32 v44, v27
	ds_read_b32 v45, v28
	v_mad_u64_u32 v[12:13], s[34:35], v12, s27, v[24:25]
	v_lshlrev_b64 v[18:19], 2, v[22:23]
	v_lshl_add_u64 v[40:41], s[0:1], 0, v[18:19]
	v_lshl_add_u64 v[42:43], s[16:17], 0, v[18:19]
	v_lshlrev_b32_e32 v13, 16, v4
	v_and_b32_e32 v4, 0xffff0000, v4
	v_lshlrev_b32_e32 v18, 16, v5
	v_and_b32_e32 v5, 0xffff0000, v5
	v_lshlrev_b32_e32 v19, 16, v6
	v_and_b32_e32 v6, 0xffff0000, v6
	v_lshlrev_b32_e32 v23, 16, v7
	v_and_b32_e32 v7, 0xffff0000, v7
	ds_write_b16 v12, v21 offset:34816
	ds_write_b16_d16_hi v12, v21 offset:35088
	ds_write_b16 v12, v29 offset:35360
	ds_write_b16_d16_hi v12, v29 offset:35632
	ds_write_b16 v12, v39 offset:35904
	ds_write_b16_d16_hi v12, v39 offset:36176
	ds_write_b16 v12, v48 offset:36448
	ds_write_b16_d16_hi v12, v48 offset:36720
	s_waitcnt lgkmcnt(9)
	v_sub_f32_e32 v12, v13, v44
	v_sub_f32_e32 v4, v4, v44
	v_sub_f32_e32 v13, v18, v44
	v_sub_f32_e32 v5, v5, v44
	v_sub_f32_e32 v18, v19, v44
	v_sub_f32_e32 v6, v6, v44
	v_sub_f32_e32 v19, v23, v44
	v_sub_f32_e32 v7, v7, v44
	s_waitcnt lgkmcnt(8)
	v_mul_f32_e32 v12, v12, v45
	v_mul_f32_e32 v4, v4, v45
	v_mul_f32_e32 v13, v13, v45
	v_mul_f32_e32 v5, v5, v45
	v_mul_f32_e32 v18, v18, v45
	v_mul_f32_e32 v6, v6, v45
	v_mul_f32_e32 v19, v19, v45
	v_mul_f32_e32 v7, v7, v45
	v_bfe_u32 v39, v26, 4, 2
	v_ashrrev_i32_e32 v21, 2, v26
	v_and_b32_e32 v23, 0x4f, v26
	v_and_b32_e32 v66, 0xffffffe0, v21
	v_mad_u64_u32 v[20:21], s[0:1], v20, s27, v[24:25]
	v_lshlrev_b32_e32 v21, 16, v0
	v_and_b32_e32 v0, 0xffff0000, v0
	s_waitcnt vmcnt(2)
	v_accvgpr_read_b32 v8, a84
	v_accvgpr_read_b32 v9, a85
	v_accvgpr_read_b32 v10, a86
	v_accvgpr_read_b32 v11, a87
	v_accvgpr_read_b32 v14, a88
	v_accvgpr_read_b32 v15, a89
	v_accvgpr_read_b32 v16, a90
	v_accvgpr_read_b32 v17, a91
	v_fma_f32 v8, v14, v12, v8
	v_fma_f32 v4, v15, v4, v9
	v_fma_f32 v9, v16, v13, v10
	v_fmac_f32_e32 v11, v17, v5
	s_waitcnt vmcnt(0)
	v_accvgpr_read_b32 v30, a92
	v_accvgpr_read_b32 v31, a93
	v_accvgpr_read_b32 v32, a94
	v_accvgpr_read_b32 v33, a95
	v_accvgpr_read_b32 v34, a96
	v_accvgpr_read_b32 v35, a97
	v_accvgpr_read_b32 v36, a98
	v_accvgpr_read_b32 v37, a99
	v_fma_f32 v5, v30, v18, v34
	v_fma_f32 v6, v31, v6, v35
	v_fma_f32 v10, v32, v19, v36
	v_fmac_f32_e32 v37, v33, v7
	v_cvt_pk_bf16_f32 v29, v8, v4
	v_cvt_pk_bf16_f32 v31, v9, v11
	v_cvt_pk_bf16_f32 v32, v5, v6
	v_cvt_pk_bf16_f32 v33, v10, v37
	s_mov_b64 exec, s[64:65]
	global_load_dwordx4 a[100:103], v[42:43], off
	global_load_dwordx4 a[104:107], v[40:41], off
	global_load_dwordx4 a[108:111], v[40:41], off offset:16
	global_load_dwordx4 a[112:115], v[42:43], off offset:16
	s_mov_b64 exec, -1
	ds_read_b32 v27, v27
	ds_read_b32 v28, v28
	v_lshl_add_u32 v30, v39, 4, 0
	v_mad_u32_u24 v64, v23, s27, v30
	v_mad_u64_u32 v[22:23], s[0:1], v22, s27, v[24:25]
	v_lshlrev_b32_e32 v23, 16, v1
	v_and_b32_e32 v1, 0xffff0000, v1
	v_lshlrev_b32_e32 v24, 16, v2
	v_and_b32_e32 v2, 0xffff0000, v2
	v_lshlrev_b32_e32 v34, 16, v3
	v_and_b32_e32 v3, 0xffff0000, v3
	ds_write_b16 v20, v29 offset:34816
	ds_write_b16_d16_hi v20, v29 offset:35088
	ds_write_b16 v20, v31 offset:35360
	ds_write_b16_d16_hi v20, v31 offset:35632
	ds_write_b16 v20, v32 offset:35904
	ds_write_b16_d16_hi v20, v32 offset:36176
	ds_write_b16 v20, v33 offset:36448
	ds_write_b16_d16_hi v20, v33 offset:36720
	s_waitcnt lgkmcnt(9)
	v_sub_f32_e32 v20, v21, v27
	v_sub_f32_e32 v0, v0, v27
	v_sub_f32_e32 v21, v23, v27
	v_sub_f32_e32 v1, v1, v27
	v_sub_f32_e32 v23, v24, v27
	v_sub_f32_e32 v2, v2, v27
	v_sub_f32_e32 v24, v34, v27
	v_sub_f32_e32 v3, v3, v27
	s_waitcnt lgkmcnt(8)
	v_mul_f32_e32 v0, v0, v28
	v_mul_f32_e32 v1, v1, v28
	v_mul_f32_e32 v23, v23, v28
	v_mul_f32_e32 v2, v2, v28
	v_mul_f32_e32 v20, v20, v28
	v_mul_f32_e32 v21, v21, v28
	v_mul_f32_e32 v24, v24, v28
	v_mul_f32_e32 v3, v3, v28
	v_or_b32_e32 v27, v66, v38
	v_mad_u64_u32 v[56:57], s[0:1], v27, s27, v[30:31]
	v_add_u32_e32 v58, s29, v27
	s_add_u32 s0, s13, s14
	s_addc_u32 s1, s18, 0
	v_mov_b32_e32 v33, v25
	v_lshlrev_b32_e32 v32, 3, v39
	v_ashrrev_i32_e32 v59, 31, v58
	v_or_b32_e32 v38, s29, v38
	s_waitcnt vmcnt(2)
	v_accvgpr_read_b32 v4, a100
	v_accvgpr_read_b32 v5, a101
	v_accvgpr_read_b32 v6, a102
	v_accvgpr_read_b32 v7, a103
	v_accvgpr_read_b32 v16, a104
	v_accvgpr_read_b32 v17, a105
	v_accvgpr_read_b32 v18, a106
	v_accvgpr_read_b32 v19, a107
	v_fma_f32 v0, v17, v0, v5
	v_fmac_f32_e32 v7, v19, v1
	s_waitcnt vmcnt(0)
	v_accvgpr_read_b32 v12, a108
	v_accvgpr_read_b32 v13, a109
	v_accvgpr_read_b32 v14, a110
	v_accvgpr_read_b32 v15, a111
	v_accvgpr_read_b32 v8, a112
	v_accvgpr_read_b32 v9, a113
	v_accvgpr_read_b32 v10, a114
	v_accvgpr_read_b32 v11, a115
	s_mov_b64 s[64:65], 0
	v_fma_f32 v1, v12, v23, v8
	v_fma_f32 v2, v13, v2, v9
	v_fma_f32 v4, v16, v20, v4
	v_fma_f32 v5, v18, v21, v6
	v_fma_f32 v6, v14, v24, v10
	v_fmac_f32_e32 v11, v15, v3
	v_cvt_pk_bf16_f32 v0, v4, v0
	v_cvt_pk_bf16_f32 v3, v5, v7
	v_cvt_pk_bf16_f32 v1, v1, v2
	v_cvt_pk_bf16_f32 v2, v6, v11
	ds_write_b16 v22, v0 offset:34816
	ds_write_b16_d16_hi v22, v0 offset:35088
	ds_write_b16 v22, v3 offset:35360
	ds_write_b16_d16_hi v22, v3 offset:35632
	ds_write_b16 v22, v1 offset:35904
	ds_write_b16_d16_hi v22, v1 offset:36176
	ds_write_b16 v22, v2 offset:36448
	ds_write_b16_d16_hi v22, v2 offset:36720
	s_waitcnt lgkmcnt(0)
	s_barrier
	ds_read_b128 v[0:3], v64 offset:34816
	ds_read_b128 v[4:7], v56
	ds_read_b128 v[8:11], v56 offset:64
	ds_read_b128 v[12:15], v64 offset:34880
	ds_read_b128 v[16:19], v64 offset:39168
	ds_read_b128 v[20:23], v64 offset:39232
	ds_read_b128 v[28:31], v64 offset:43520
	ds_read_b128 v[34:37], v64 offset:43584
	ds_read_b128 v[40:43], v64 offset:47872
	ds_read_b128 v[44:47], v64 offset:47936
	s_waitcnt lgkmcnt(8)
	v_mfma_f32_16x16x32_bf16 a[0:3], v[0:3], v[4:7], 0
	s_waitcnt lgkmcnt(5)
	v_mfma_f32_16x16x32_bf16 a[4:7], v[16:19], v[4:7], 0
	s_waitcnt lgkmcnt(3)
	v_mfma_f32_16x16x32_bf16 a[8:11], v[28:31], v[4:7], 0
	s_waitcnt lgkmcnt(1)
	v_mfma_f32_16x16x32_bf16 a[12:15], v[40:43], v[4:7], 0
	ds_read_b128 v[4:7], v56 offset:4352
	ds_read_b128 v[48:51], v56 offset:4416
	s_waitcnt lgkmcnt(1)
	v_mfma_f32_16x16x32_bf16 a[16:19], v[0:3], v[4:7], 0
	v_and_b32_e32 v0, 64, v26
	v_lshlrev_b32_e32 v24, 1, v0
	v_add_u32_e32 v0, s30, v27
	v_mfma_f32_16x16x32_bf16 a[20:23], v[16:19], v[4:7], 0
	v_ashrrev_i32_e32 v1, 31, v0
	v_lshl_add_u64 v[60:61], v[0:1], 2, s[72:73]
	v_mfma_f32_16x16x32_bf16 a[24:27], v[28:31], v[4:7], 0
	ds_read_b128 v[26:29], v64 offset:34944
	v_lshlrev_b64 v[30:31], 11, v[58:59]
	v_mfma_f32_16x16x32_bf16 a[28:31], v[40:43], v[4:7], 0
	v_mfma_f32_16x16x32_bf16 a[4:7], v[20:23], v[8:11], a[4:7]
	s_waitcnt lgkmcnt(1)
	v_mfma_f32_16x16x32_bf16 a[20:23], v[20:23], v[48:51], a[20:23]
	ds_read_b128 v[20:23], v56 offset:128
	ds_read_b128 v[40:43], v64 offset:39296
	v_mfma_f32_16x16x32_bf16 a[0:3], v[12:15], v[8:11], a[0:3]
	v_mfma_f32_16x16x32_bf16 a[8:11], v[34:37], v[8:11], a[8:11]
	v_mfma_f32_16x16x32_bf16 a[12:15], v[44:47], v[8:11], a[12:15]
	v_mfma_f32_16x16x32_bf16 a[16:19], v[12:15], v[48:51], a[16:19]
	v_lshl_add_u64 v[12:13], s[0:1], 0, v[24:25]
	v_lshl_add_u64 v[62:63], v[12:13], 0, v[32:33]
	s_add_u32 s0, s19, s14
	v_mfma_f32_16x16x32_bf16 a[32:35], v[34:37], v[48:51], a[24:27]
	s_addc_u32 s1, s20, 0
	s_add_i32 s28, s28, s3
	s_add_i32 s21, s21, s22
	v_mfma_f32_16x16x32_bf16 a[28:31], v[44:47], v[48:51], a[28:31]
	ds_read_b128 v[44:47], v64 offset:43648
	ds_read_b128 v[16:19], v56 offset:192
	ds_read_b128 v[0:3], v64 offset:35008
	ds_read_b128 v[48:51], v64 offset:48000
	ds_read_b128 v[4:7], v64 offset:39360
	ds_read_b128 v[8:11], v64 offset:43712
	ds_read_b128 v[52:55], v56 offset:4480
	ds_read_b128 v[12:15], v64 offset:48064
	v_lshl_add_u64 v[64:65], v[62:63], 0, v[30:31]
	s_waitcnt lgkmcnt(9)
	v_mfma_f32_16x16x32_bf16 a[36:39], v[26:29], v[20:23], a[0:3]
	global_load_dwordx2 v[36:37], v[64:65], off
	global_load_dwordx2 v[34:35], v[64:65], off offset:32
	global_load_dwordx2 v[30:31], v[64:65], off offset:64
	s_waitcnt lgkmcnt(8)
	v_mfma_f32_16x16x32_bf16 a[40:43], v[40:43], v[20:23], a[4:7]
	global_load_dword v39, v[60:61], off offset:64
	s_add_i32 s23, s23, s24
	s_cmpk_lt_i32 s28, 0x400
	s_waitcnt lgkmcnt(7)
	v_mfma_f32_16x16x32_bf16 a[44:47], v[44:47], v[20:23], a[8:11]
	s_waitcnt lgkmcnt(4)
	v_mfma_f32_16x16x32_bf16 a[48:51], v[48:51], v[20:23], a[12:15]
	ds_read_b128 v[20:23], v56 offset:4544
	global_load_dword v56, v[60:61], off
	s_waitcnt lgkmcnt(2)
	v_mfma_f32_16x16x32_bf16 a[24:27], v[26:29], v[52:55], a[16:19]
	v_add_u32_e32 v26, 16, v58
	global_load_dwordx2 v[28:29], v[64:65], off offset:96
	v_ashrrev_i32_e32 v27, 31, v26
	v_lshlrev_b64 v[26:27], 11, v[26:27]
	v_mfma_f32_16x16x32_bf16 a[16:19], v[40:43], v[52:55], a[20:23]
	v_lshl_add_u64 v[40:41], v[62:63], 0, v[26:27]
	global_load_dwordx2 v[26:27], v[40:41], off
	v_add_u32_e32 v42, v38, v66
	v_mfma_f32_16x16x32_bf16 a[4:7], v[44:47], v[52:55], a[32:35]
	v_or_b32_e32 v44, 16, v42
	v_ashrrev_i32_e32 v43, 31, v42
	v_ashrrev_i32_e32 v45, 31, v44
	v_mfma_f32_16x16x32_bf16 a[8:11], v[0:3], v[16:19], a[36:39]
	s_waitcnt vmcnt(4)
	v_lshlrev_b32_e32 v46, 16, v31
	v_mfma_f32_16x16x32_bf16 a[12:15], v[4:7], v[16:19], a[40:43]
	v_and_b32_e32 v31, 0xffff0000, v31
	s_waitcnt vmcnt(1)
	v_lshlrev_b32_e32 v47, 16, v28
	v_mfma_f32_16x16x32_bf16 a[20:23], v[8:11], v[16:19], a[44:47]
	v_and_b32_e32 v28, 0xffff0000, v28
	s_waitcnt lgkmcnt(0)
	v_mfma_f32_16x16x32_bf16 a[24:27], v[0:3], v[20:23], a[24:27]
	v_lshl_add_u64 v[0:1], s[0:1], 0, v[24:25]
	v_lshl_add_u64 v[0:1], v[0:1], 0, v[32:33]
	v_mfma_f32_16x16x32_bf16 a[16:19], v[4:7], v[20:23], a[16:19]
	v_mfma_f32_16x16x32_bf16 a[4:7], v[8:11], v[20:23], a[4:7]
	global_load_dwordx2 v[8:9], v[40:41], off offset:32
	global_load_dwordx2 v[4:5], v[40:41], off offset:64
	global_load_dwordx2 v[2:3], v[40:41], off offset:96
	v_accvgpr_read_b32 v10, a8
	v_accvgpr_read_b32 v11, a9
	v_mfma_f32_16x16x32_bf16 a[0:3], v[48:51], v[52:55], a[28:31]
	v_lshlrev_b32_e32 v41, 16, v36
	v_add_f32_e32 v10, v56, v10
	v_and_b32_e32 v36, 0xffff0000, v36
	v_mfma_f32_16x16x32_bf16 a[28:31], v[12:15], v[16:19], a[48:51]
	v_lshlrev_b64 v[16:17], 11, v[42:43]
	v_lshlrev_b64 v[18:19], 11, v[44:45]
	v_add_f32_e32 v11, v56, v11
	v_mfma_f32_16x16x32_bf16 a[0:3], v[12:15], v[20:23], a[0:3]
	v_accvgpr_read_b32 v12, a10
	v_accvgpr_read_b32 v13, a11
	v_accvgpr_read_b32 v14, a12
	v_accvgpr_read_b32 v15, a13
	v_mul_f32_e32 v10, v10, v41
	v_lshl_add_u64 v[6:7], v[0:1], 0, v[16:17]
	v_lshl_add_u64 v[0:1], v[0:1], 0, v[18:19]
	v_accvgpr_read_b32 v16, a14
	v_accvgpr_read_b32 v17, a15
	v_accvgpr_read_b32 v18, a20
	v_accvgpr_read_b32 v19, a21
	v_lshlrev_b32_e32 v42, 16, v37
	v_add_f32_e32 v12, v56, v12
	v_and_b32_e32 v37, 0xffff0000, v37
	v_add_f32_e32 v13, v56, v13
	v_lshlrev_b32_e32 v43, 16, v34
	v_add_f32_e32 v14, v56, v14
	v_and_b32_e32 v34, 0xffff0000, v34
	v_add_f32_e32 v15, v56, v15
	v_mul_f32_e32 v11, v11, v36
	v_cvt_pk_bf16_f32 v10, v10, v11
	v_accvgpr_read_b32 v20, a22
	v_accvgpr_read_b32 v21, a23
	v_accvgpr_read_b32 v22, a28
	v_accvgpr_read_b32 v23, a29
	v_lshlrev_b32_e32 v44, 16, v35
	v_add_f32_e32 v16, v56, v16
	v_and_b32_e32 v35, 0xffff0000, v35
	v_add_f32_e32 v17, v56, v17
	v_lshlrev_b32_e32 v45, 16, v30
	v_add_f32_e32 v18, v56, v18
	v_and_b32_e32 v30, 0xffff0000, v30
	v_add_f32_e32 v19, v56, v19
	v_mul_f32_e32 v12, v12, v42
	v_mul_f32_e32 v13, v13, v37
	v_mul_f32_e32 v14, v14, v43
	v_mul_f32_e32 v15, v15, v34
	v_cvt_pk_bf16_f32 v11, v12, v13
	global_store_dwordx2 v[6:7], v[10:11], off
	v_cvt_pk_bf16_f32 v10, v14, v15
	v_accvgpr_read_b32 v24, a30
	v_accvgpr_read_b32 v32, a31
	v_add_f32_e32 v20, v56, v20
	v_add_f32_e32 v21, v56, v21
	v_add_f32_e32 v22, v56, v22
	v_add_f32_e32 v23, v56, v23
	v_mul_f32_e32 v16, v16, v44
	v_mul_f32_e32 v17, v17, v35
	v_mul_f32_e32 v18, v18, v45
	v_mul_f32_e32 v19, v19, v30
	v_cvt_pk_bf16_f32 v11, v16, v17
	global_store_dwordx2 v[6:7], v[10:11], off offset:32
	v_cvt_pk_bf16_f32 v10, v18, v19
	v_lshlrev_b32_e32 v48, 16, v29
	v_add_f32_e32 v24, v56, v24
	v_and_b32_e32 v29, 0xffff0000, v29
	v_add_f32_e32 v32, v56, v32
	v_mul_f32_e32 v20, v20, v46
	v_mul_f32_e32 v21, v21, v31
	v_mul_f32_e32 v22, v22, v47
	v_mul_f32_e32 v23, v23, v28
	v_cvt_pk_bf16_f32 v11, v20, v21
	global_store_dwordx2 v[6:7], v[10:11], off offset:64
	v_cvt_pk_bf16_f32 v10, v22, v23
	v_mul_f32_e32 v24, v24, v48
	v_mul_f32_e32 v28, v32, v29
	v_cvt_pk_bf16_f32 v11, v24, v28
	global_store_dwordx2 v[6:7], v[10:11], off offset:96
	v_accvgpr_read_b32 v10, a27
	v_accvgpr_read_b32 v33, a24
	v_accvgpr_read_b32 v38, a25
	v_accvgpr_read_b32 v40, a26
	s_waitcnt vmcnt(7)
	v_and_b32_e32 v7, 0xffff0000, v27
	v_add_f32_e32 v10, v39, v10
	v_lshlrev_b32_e32 v49, 16, v26
	v_add_f32_e32 v33, v39, v33
	v_and_b32_e32 v26, 0xffff0000, v26
	v_add_f32_e32 v38, v39, v38
	v_lshlrev_b32_e32 v50, 16, v27
	v_add_f32_e32 v40, v39, v40
	v_mul_f32_e32 v7, v10, v7
	v_mul_f32_e32 v29, v33, v49
	v_mul_f32_e32 v26, v38, v26
	v_mul_f32_e32 v30, v40, v50
	v_cvt_pk_bf16_f32 v6, v29, v26
	v_cvt_pk_bf16_f32 v7, v30, v7
	global_store_dwordx2 v[0:1], v[6:7], off
	v_accvgpr_read_b32 v7, a16
	s_waitcnt vmcnt(7)
	v_lshlrev_b32_e32 v6, 16, v8
	v_add_f32_e32 v7, v39, v7
	v_mul_f32_e32 v6, v7, v6
	v_and_b32_e32 v7, 0xffff0000, v8
	v_accvgpr_read_b32 v8, a17
	v_add_f32_e32 v8, v39, v8
	v_mul_f32_e32 v7, v8, v7
	v_accvgpr_read_b32 v8, a18
	v_cvt_pk_bf16_f32 v6, v6, v7
	v_lshlrev_b32_e32 v7, 16, v9
	v_add_f32_e32 v8, v39, v8
	v_mul_f32_e32 v7, v8, v7
	v_and_b32_e32 v8, 0xffff0000, v9
	v_accvgpr_read_b32 v9, a19
	v_add_f32_e32 v9, v39, v9
	v_mul_f32_e32 v8, v9, v8
	v_cvt_pk_bf16_f32 v7, v7, v8
	global_store_dwordx2 v[0:1], v[6:7], off offset:32
	v_accvgpr_read_b32 v7, a4
	s_waitcnt vmcnt(7)
	v_lshlrev_b32_e32 v6, 16, v4
	v_add_f32_e32 v7, v39, v7
	v_mul_f32_e32 v6, v7, v6
	v_accvgpr_read_b32 v7, a5
	v_and_b32_e32 v4, 0xffff0000, v4
	v_add_f32_e32 v7, v39, v7
	v_mul_f32_e32 v4, v7, v4
	v_accvgpr_read_b32 v7, a6
	v_cvt_pk_bf16_f32 v4, v6, v4
	v_lshlrev_b32_e32 v6, 16, v5
	v_add_f32_e32 v7, v39, v7
	v_mul_f32_e32 v6, v7, v6
	v_accvgpr_read_b32 v7, a7
	v_and_b32_e32 v5, 0xffff0000, v5
	v_add_f32_e32 v7, v39, v7
	v_mul_f32_e32 v5, v7, v5
	v_cvt_pk_bf16_f32 v5, v6, v5
	global_store_dwordx2 v[0:1], v[4:5], off offset:64
	v_accvgpr_read_b32 v5, a0
	s_waitcnt vmcnt(7)
	v_lshlrev_b32_e32 v4, 16, v2
	v_add_f32_e32 v5, v39, v5
	v_mul_f32_e32 v4, v5, v4
	v_accvgpr_read_b32 v5, a1
	v_and_b32_e32 v2, 0xffff0000, v2
	v_add_f32_e32 v5, v39, v5
	v_mul_f32_e32 v2, v5, v2
	v_accvgpr_read_b32 v5, a2
	v_cvt_pk_bf16_f32 v2, v4, v2
	v_lshlrev_b32_e32 v4, 16, v3
	v_add_f32_e32 v5, v39, v5
	v_mul_f32_e32 v4, v5, v4
	v_accvgpr_read_b32 v5, a3
	v_and_b32_e32 v3, 0xffff0000, v3
	v_add_f32_e32 v5, v39, v5
	v_mul_f32_e32 v3, v5, v3
	v_cvt_pk_bf16_f32 v3, v4, v3
	global_store_dwordx2 v[0:1], v[2:3], off offset:96
	s_barrier
	s_cbranch_scc0 .LBB0_1212
